# v41 plus 64-bit accumulator zeroing moves and removal of s_nop 2 before cvt in epilogues without transcendentals (P6 P7 P10 P13)
# baseline (speedup 1.0000x reference)
.LBB0_115:
	s_ashr_i32 s93, s92, 31
	s_lshl_b64 s[18:19], s[92:93], 21
	s_add_u32 s22, s86, s18
	s_addc_u32 s23, s87, s19
	s_and_b64 s[18:19], s[8:9], exec
	s_cselect_b32 s89, s23, s95
	s_cselect_b32 s93, s22, s94
	s_ashr_i32 s85, s84, 31
	s_lshl_b64 s[18:19], s[84:85], 21
	s_add_u32 s18, s29, s18
	s_addc_u32 s19, s76, s19
	s_and_b64 s[34:35], s[8:9], exec
	s_cselect_b32 s85, s19, s97
	s_cselect_b32 s34, s18, s96
	s_add_u32 s35, s96, 0x100
	v_mov_b32_e32 v0, 0
	s_addc_u32 s36, s97, 0
	s_mov_b32 s37, -2
	v_mov_b32_e32 v1, v0
	v_mov_b64_e32 v[2:3], 0
	v_mov_b64_e32 v[4:5], 0
	v_mov_b64_e32 v[6:7], 0
	v_mov_b64_e32 v[8:9], 0
	v_mov_b64_e32 v[10:11], 0
	v_mov_b64_e32 v[12:13], 0
	v_mov_b64_e32 v[14:15], 0
	v_mov_b64_e32 v[16:17], 0
	v_mov_b64_e32 v[18:19], 0
	v_mov_b64_e32 v[20:21], 0
	v_mov_b64_e32 v[22:23], 0
	v_mov_b64_e32 v[24:25], 0
	v_mov_b64_e32 v[26:27], 0
	v_mov_b64_e32 v[28:29], 0
	v_mov_b64_e32 v[30:31], 0
	v_mov_b64_e32 v[32:33], 0
	v_mov_b64_e32 v[34:35], 0
	v_mov_b64_e32 v[36:37], 0
	v_mov_b64_e32 v[38:39], 0
	v_mov_b64_e32 v[40:41], 0
	v_mov_b64_e32 v[42:43], 0
	v_mov_b64_e32 v[44:45], 0
	v_mov_b64_e32 v[46:47], 0
	v_mov_b64_e32 v[48:49], 0
	v_mov_b64_e32 v[50:51], 0
	v_mov_b64_e32 v[52:53], 0
	v_mov_b64_e32 v[54:55], 0
	v_mov_b64_e32 v[56:57], 0
	v_mov_b64_e32 v[58:59], 0
	v_mov_b64_e32 v[60:61], 0
	v_mov_b64_e32 v[62:63], 0
	v_mov_b64_e32 v[64:65], 0
	v_mov_b64_e32 v[66:67], 0
	v_mov_b64_e32 v[68:69], 0
	v_mov_b64_e32 v[70:71], 0
	v_mov_b64_e32 v[72:73], 0
	v_mov_b64_e32 v[74:75], 0
	v_mov_b64_e32 v[76:77], 0
	v_mov_b64_e32 v[78:79], 0
	v_mov_b64_e32 v[80:81], 0
	v_mov_b64_e32 v[82:83], 0
	v_mov_b64_e32 v[84:85], 0
	v_mov_b64_e32 v[86:87], 0
	v_mov_b64_e32 v[88:89], 0
	v_mov_b64_e32 v[90:91], 0
	v_mov_b64_e32 v[92:93], 0
	v_mov_b64_e32 v[94:95], 0
	v_mov_b64_e32 v[96:97], 0
	v_mov_b64_e32 v[98:99], 0
	v_mov_b64_e32 v[100:101], 0
	v_mov_b64_e32 v[102:103], 0
	v_mov_b64_e32 v[104:105], 0
	v_mov_b64_e32 v[106:107], 0
	v_mov_b64_e32 v[108:109], 0
	v_mov_b64_e32 v[110:111], 0
	v_mov_b64_e32 v[112:113], 0
	v_mov_b64_e32 v[114:115], 0
	v_mov_b64_e32 v[116:117], 0
	v_mov_b64_e32 v[118:119], 0
	v_mov_b64_e32 v[120:121], 0
	v_mov_b64_e32 v[122:123], 0
	v_mov_b64_e32 v[124:125], 0
	v_mov_b64_e32 v[126:127], 0
	s_cmpk_lt_u32 s97, 0x100
	s_cbranch_scc1 .Lmy_prio_skip0
	s_setprio 1

.LBB0_520:
	s_ashr_i32 s13, s12, 31
	s_lshl_b64 s[18:19], s[12:13], 20
	s_add_u32 s18, s33, s18
	s_addc_u32 s19, s52, s19
	s_and_b64 s[34:35], s[0:1], exec
	s_cselect_b32 s13, s19, s47
	s_cselect_b32 s64, s18, s46
	s_ashr_i32 s11, s10, 31
	s_lshl_b64 s[34:35], s[10:11], 20
	v_readlane_b32 s11, v254, 40
	s_add_u32 s44, s11, s34
	v_readlane_b32 s11, v254, 41
	s_addc_u32 s45, s11, s35
	s_and_b64 s[34:35], s[0:1], exec
	s_cselect_b32 s11, s45, s49
	s_cselect_b32 s65, s44, s48
	s_add_u32 s46, s46, 0x80080
	s_addc_u32 s47, s47, 0
	s_add_u32 s34, s48, 0x100
	v_mov_b32_e32 v0, 0
	s_addc_u32 s35, s49, 0
	s_mov_b32 s36, -2
	v_mov_b32_e32 v1, v0
	v_mov_b64_e32 v[2:3], 0
	v_mov_b64_e32 v[4:5], 0
	v_mov_b64_e32 v[6:7], 0
	v_mov_b64_e32 v[8:9], 0
	v_mov_b64_e32 v[10:11], 0
	v_mov_b64_e32 v[12:13], 0
	v_mov_b64_e32 v[14:15], 0
	v_mov_b64_e32 v[16:17], 0
	v_mov_b64_e32 v[18:19], 0
	v_mov_b64_e32 v[20:21], 0
	v_mov_b64_e32 v[22:23], 0
	v_mov_b64_e32 v[24:25], 0
	v_mov_b64_e32 v[26:27], 0
	v_mov_b64_e32 v[28:29], 0
	v_mov_b64_e32 v[30:31], 0
	v_mov_b64_e32 v[32:33], 0
	v_mov_b64_e32 v[34:35], 0
	v_mov_b64_e32 v[36:37], 0
	v_mov_b64_e32 v[38:39], 0
	v_mov_b64_e32 v[40:41], 0
	v_mov_b64_e32 v[42:43], 0
	v_mov_b64_e32 v[44:45], 0
	v_mov_b64_e32 v[46:47], 0
	v_mov_b64_e32 v[48:49], 0
	v_mov_b64_e32 v[50:51], 0
	v_mov_b64_e32 v[52:53], 0
	v_mov_b64_e32 v[54:55], 0
	v_mov_b64_e32 v[56:57], 0
	v_mov_b64_e32 v[58:59], 0
	v_mov_b64_e32 v[60:61], 0
	v_mov_b64_e32 v[62:63], 0
	v_mov_b64_e32 v[64:65], 0
	v_mov_b64_e32 v[66:67], 0
	v_mov_b64_e32 v[68:69], 0
	v_mov_b64_e32 v[70:71], 0
	v_mov_b64_e32 v[72:73], 0
	v_mov_b64_e32 v[74:75], 0
	v_mov_b64_e32 v[76:77], 0
	v_mov_b64_e32 v[78:79], 0
	v_mov_b64_e32 v[80:81], 0
	v_mov_b64_e32 v[82:83], 0
	v_mov_b64_e32 v[84:85], 0
	v_mov_b64_e32 v[86:87], 0
	v_mov_b64_e32 v[88:89], 0
	v_mov_b64_e32 v[90:91], 0
	v_mov_b64_e32 v[92:93], 0
	v_mov_b64_e32 v[94:95], 0
	v_mov_b64_e32 v[96:97], 0
	v_mov_b64_e32 v[98:99], 0
	v_mov_b64_e32 v[100:101], 0
	v_mov_b64_e32 v[102:103], 0
	v_mov_b64_e32 v[104:105], 0
	v_mov_b64_e32 v[106:107], 0
	v_mov_b64_e32 v[108:109], 0
	v_mov_b64_e32 v[110:111], 0
	v_mov_b64_e32 v[112:113], 0
	v_mov_b64_e32 v[114:115], 0
	v_mov_b64_e32 v[116:117], 0
	v_mov_b64_e32 v[118:119], 0
	v_mov_b64_e32 v[120:121], 0
	v_mov_b64_e32 v[122:123], 0
	v_mov_b64_e32 v[124:125], 0
	v_mov_b64_e32 v[126:127], 0
	s_cmpk_lt_u32 s97, 0x100
	s_cbranch_scc1 .Lmy_prio_skip1
	s_setprio 1

.LBB0_524:
	v_lshl_add_u32 v152, s16, 8, v146
	v_lshl_or_b32 v144, s63, 8, v148
	v_ashrrev_i32_e32 v153, 31, v152
	v_ashrrev_i32_e32 v145, 31, v144
	v_lshlrev_b64 v[154:155], 13, v[152:153]
	v_lshl_add_u64 v[154:155], s[74:75], 0, v[154:155]
	v_lshlrev_b64 v[156:157], 1, v[144:145]
	v_lshl_add_u64 v[144:145], v[154:155], 0, v[156:157]
	v_cvt_pk_bf16_f32 v124, v124, v125
	v_cvt_pk_bf16_f32 v125, v126, v127
	v_cvt_pk_bf16_f32 v126, v120, v121
	v_cvt_pk_bf16_f32 v127, v122, v123
	global_store_dwordx4 v[144:145], v[124:127], off
	v_cvt_pk_bf16_f32 v112, v112, v113
	v_cvt_pk_bf16_f32 v113, v114, v115
	v_cvt_pk_bf16_f32 v114, v104, v105
	v_or_b32_e32 v104, 16, v152
	v_ashrrev_i32_e32 v105, 31, v104
	v_lshlrev_b64 v[104:105], 13, v[104:105]
	v_lshl_add_u64 v[104:105], s[74:75], 0, v[104:105]
	v_cvt_pk_bf16_f32 v115, v106, v107
	global_store_dwordx4 v[144:145], v[112:115], off offset:256
	s_mov_b32 s11, 0x100000
	s_mov_b64 s[34:35], 0x100000
	v_lshl_add_u64 v[112:113], v[104:105], 0, v[156:157]
	v_cvt_pk_bf16_f32 v104, v116, v117
	v_cvt_pk_bf16_f32 v105, v118, v119
	v_cvt_pk_bf16_f32 v106, v108, v109
	v_cvt_pk_bf16_f32 v107, v110, v111
	global_store_dwordx4 v[112:113], v[104:107], off
	v_cvt_pk_bf16_f32 v96, v96, v97
	v_cvt_pk_bf16_f32 v97, v98, v99
	v_cvt_pk_bf16_f32 v98, v88, v89
	v_or_b32_e32 v88, 32, v152
	v_ashrrev_i32_e32 v89, 31, v88
	v_lshlrev_b64 v[88:89], 13, v[88:89]
	v_lshl_add_u64 v[88:89], s[74:75], 0, v[88:89]
	v_cvt_pk_bf16_f32 v99, v90, v91
	global_store_dwordx4 v[112:113], v[96:99], off offset:256
	s_nop 1
	v_lshl_add_u64 v[96:97], v[88:89], 0, v[156:157]
	v_cvt_pk_bf16_f32 v88, v100, v101
	v_cvt_pk_bf16_f32 v89, v102, v103
	v_cvt_pk_bf16_f32 v90, v92, v93
	v_cvt_pk_bf16_f32 v91, v94, v95
	global_store_dwordx4 v[96:97], v[88:91], off
	v_cvt_pk_bf16_f32 v80, v80, v81
	v_cvt_pk_bf16_f32 v81, v82, v83
	v_cvt_pk_bf16_f32 v82, v72, v73
	v_or_b32_e32 v72, 48, v152
	v_ashrrev_i32_e32 v73, 31, v72
	v_lshlrev_b64 v[72:73], 13, v[72:73]
	v_lshl_add_u64 v[72:73], s[74:75], 0, v[72:73]
	v_cvt_pk_bf16_f32 v83, v74, v75
	global_store_dwordx4 v[96:97], v[80:83], off offset:256
	s_nop 1
	v_lshl_add_u64 v[80:81], v[72:73], 0, v[156:157]
	v_cvt_pk_bf16_f32 v72, v84, v85
	v_cvt_pk_bf16_f32 v73, v86, v87
	v_cvt_pk_bf16_f32 v74, v76, v77
	v_cvt_pk_bf16_f32 v75, v78, v79
	global_store_dwordx4 v[80:81], v[72:75], off
	v_cvt_pk_bf16_f32 v68, v68, v69
	v_cvt_pk_bf16_f32 v69, v70, v71
	v_cvt_pk_bf16_f32 v70, v64, v65
	v_cvt_pk_bf16_f32 v71, v66, v67
	global_store_dwordx4 v[80:81], v[68:71], off offset:256
	v_cvt_pk_bf16_f32 v60, v60, v61
	v_cvt_pk_bf16_f32 v61, v62, v63
	v_cvt_pk_bf16_f32 v62, v56, v57
	v_add_co_u32_e32 v56, vcc, s11, v144
	v_lshl_add_u64 v[64:65], v[144:145], 0, s[34:35]
	s_nop 0
	v_addc_co_u32_e32 v57, vcc, 0, v145, vcc
	s_mov_b32 s11, 0x120000
	v_cvt_pk_bf16_f32 v63, v58, v59
	global_store_dwordx4 v[56:57], v[60:63], off
	v_cvt_pk_bf16_f32 v48, v48, v49
	v_cvt_pk_bf16_f32 v49, v50, v51
	v_cvt_pk_bf16_f32 v50, v40, v41
	v_cvt_pk_bf16_f32 v51, v42, v43
	global_store_dwordx4 v[64:65], v[48:51], off offset:256
	s_mov_b64 s[34:35], 0x120000
	v_cvt_pk_bf16_f32 v40, v52, v53
	v_cvt_pk_bf16_f32 v41, v54, v55
	v_cvt_pk_bf16_f32 v42, v44, v45
	v_add_co_u32_e32 v44, vcc, s11, v144
	v_lshl_add_u64 v[48:49], v[144:145], 0, s[34:35]
	s_nop 0
	v_addc_co_u32_e32 v45, vcc, 0, v145, vcc
	s_mov_b32 s11, 0x140000
	v_cvt_pk_bf16_f32 v43, v46, v47
	global_store_dwordx4 v[44:45], v[40:43], off
	v_cvt_pk_bf16_f32 v32, v32, v33
	v_cvt_pk_bf16_f32 v33, v34, v35
	v_cvt_pk_bf16_f32 v34, v24, v25
	v_cvt_pk_bf16_f32 v35, v26, v27
	global_store_dwordx4 v[48:49], v[32:35], off offset:256
	s_mov_b64 s[34:35], 0x140000
	v_cvt_pk_bf16_f32 v24, v36, v37
	v_cvt_pk_bf16_f32 v25, v38, v39
	v_cvt_pk_bf16_f32 v26, v28, v29
	v_add_co_u32_e32 v28, vcc, s11, v144
	v_lshl_add_u64 v[32:33], v[144:145], 0, s[34:35]
	s_nop 0
	v_addc_co_u32_e32 v29, vcc, 0, v145, vcc
	s_mov_b32 s11, 0x160000
	v_cvt_pk_bf16_f32 v27, v30, v31
	global_store_dwordx4 v[28:29], v[24:27], off
	v_cvt_pk_bf16_f32 v16, v16, v17
	v_cvt_pk_bf16_f32 v17, v18, v19
	v_cvt_pk_bf16_f32 v18, v8, v9
	v_cvt_pk_bf16_f32 v19, v10, v11
	global_store_dwordx4 v[32:33], v[16:19], off offset:256
	v_cvt_pk_bf16_f32 v8, v20, v21
	v_cvt_pk_bf16_f32 v9, v22, v23
	v_cvt_pk_bf16_f32 v10, v12, v13
	v_add_co_u32_e32 v12, vcc, s11, v144
	s_mov_b64 s[34:35], 0x160000
	s_nop 0
	v_addc_co_u32_e32 v13, vcc, 0, v145, vcc
	v_lshl_add_u64 v[16:17], v[144:145], 0, s[34:35]
	s_andn2_b64 vcc, exec, s[0:1]
	s_mov_b64 s[0:1], -1
	v_cvt_pk_bf16_f32 v11, v14, v15
	global_store_dwordx4 v[12:13], v[8:11], off
	v_cvt_pk_bf16_f32 v4, v4, v5
	v_cvt_pk_bf16_f32 v5, v6, v7
	v_cvt_pk_bf16_f32 v6, v0, v1
	v_cvt_pk_bf16_f32 v7, v2, v3
	global_store_dwordx4 v[16:17], v[4:7], off offset:256
	s_cbranch_vccnz .LBB0_513
	s_andn2_b64 vcc, exec, s[4:5]
	s_cbranch_vccnz .LBB0_512
	s_barrier
	s_branch .LBB0_512

.LBB0_599:
	s_ashr_i32 s17, s16, 31
	s_lshl_b64 s[34:35], s[16:17], 21
	s_add_u32 s44, s33, s34
	s_addc_u32 s45, s54, s35
	s_and_b64 s[34:35], s[0:1], exec
	s_cselect_b32 s17, s45, s49
	s_cselect_b32 s66, s44, s48
	s_ashr_i32 s13, s12, 31
	s_lshl_b64 s[34:35], s[12:13], 21
	s_add_u32 s46, s92, s34
	v_readlane_b32 s13, v254, 42
	s_addc_u32 s47, s13, s35
	s_and_b64 s[34:35], s[0:1], exec
	s_cselect_b32 s13, s47, s51
	s_cselect_b32 s67, s46, s50
	s_add_u32 s48, s48, 0x100080
	s_addc_u32 s49, s49, 0
	s_add_u32 s34, s50, 0x100
	v_mov_b32_e32 v0, 0
	s_addc_u32 s35, s51, 0
	s_mov_b32 s36, -2
	v_mov_b32_e32 v1, v0
	v_mov_b64_e32 v[2:3], 0
	v_mov_b64_e32 v[4:5], 0
	v_mov_b64_e32 v[6:7], 0
	v_mov_b64_e32 v[8:9], 0
	v_mov_b64_e32 v[10:11], 0
	v_mov_b64_e32 v[12:13], 0
	v_mov_b64_e32 v[14:15], 0
	v_mov_b64_e32 v[16:17], 0
	v_mov_b64_e32 v[18:19], 0
	v_mov_b64_e32 v[20:21], 0
	v_mov_b64_e32 v[22:23], 0
	v_mov_b64_e32 v[24:25], 0
	v_mov_b64_e32 v[26:27], 0
	v_mov_b64_e32 v[28:29], 0
	v_mov_b64_e32 v[30:31], 0
	v_mov_b64_e32 v[32:33], 0
	v_mov_b64_e32 v[34:35], 0
	v_mov_b64_e32 v[36:37], 0
	v_mov_b64_e32 v[38:39], 0
	v_mov_b64_e32 v[40:41], 0
	v_mov_b64_e32 v[42:43], 0
	v_mov_b64_e32 v[44:45], 0
	v_mov_b64_e32 v[46:47], 0
	v_mov_b64_e32 v[48:49], 0
	v_mov_b64_e32 v[50:51], 0
	v_mov_b64_e32 v[52:53], 0
	v_mov_b64_e32 v[54:55], 0
	v_mov_b64_e32 v[56:57], 0
	v_mov_b64_e32 v[58:59], 0
	v_mov_b64_e32 v[60:61], 0
	v_mov_b64_e32 v[62:63], 0
	v_mov_b64_e32 v[64:65], 0
	v_mov_b64_e32 v[66:67], 0
	v_mov_b64_e32 v[68:69], 0
	v_mov_b64_e32 v[70:71], 0
	v_mov_b64_e32 v[72:73], 0
	v_mov_b64_e32 v[74:75], 0
	v_mov_b64_e32 v[76:77], 0
	v_mov_b64_e32 v[78:79], 0
	v_mov_b64_e32 v[80:81], 0
	v_mov_b64_e32 v[82:83], 0
	v_mov_b64_e32 v[84:85], 0
	v_mov_b64_e32 v[86:87], 0
	v_mov_b64_e32 v[88:89], 0
	v_mov_b64_e32 v[90:91], 0
	v_mov_b64_e32 v[92:93], 0
	v_mov_b64_e32 v[94:95], 0
	v_mov_b64_e32 v[96:97], 0
	v_mov_b64_e32 v[98:99], 0
	v_mov_b64_e32 v[100:101], 0
	v_mov_b64_e32 v[102:103], 0
	v_mov_b64_e32 v[104:105], 0
	v_mov_b64_e32 v[106:107], 0
	v_mov_b64_e32 v[108:109], 0
	v_mov_b64_e32 v[110:111], 0
	v_mov_b64_e32 v[112:113], 0
	v_mov_b64_e32 v[114:115], 0
	v_mov_b64_e32 v[116:117], 0
	v_mov_b64_e32 v[118:119], 0
	v_mov_b64_e32 v[120:121], 0
	v_mov_b64_e32 v[122:123], 0
	v_mov_b64_e32 v[124:125], 0
	v_mov_b64_e32 v[126:127], 0
	s_cmpk_lt_u32 s97, 0x100
	s_cbranch_scc1 .Lmy_prio_skip2
	s_setprio 1

.LBB0_603:
	v_lshl_add_u32 v152, s18, 8, v146
	v_lshl_or_b32 v144, s65, 8, v148
	v_ashrrev_i32_e32 v153, 31, v152
	v_ashrrev_i32_e32 v145, 31, v144
	v_lshlrev_b64 v[154:155], 13, v[152:153]
	v_lshl_add_u64 v[154:155], s[6:7], 0, v[154:155]
	v_lshlrev_b64 v[156:157], 1, v[144:145]
	v_lshl_add_u64 v[144:145], v[154:155], 0, v[156:157]
	s_nop 2
	v_cvt_pk_bf16_f32 v124, v124, v125
	s_nop 2
	v_cvt_pk_bf16_f32 v125, v126, v127
	s_nop 2
	v_cvt_pk_bf16_f32 v126, v120, v121
	s_nop 2
	v_cvt_pk_bf16_f32 v127, v122, v123
	global_store_dwordx4 v[144:145], v[124:127], off
	s_nop 2
	v_cvt_pk_bf16_f32 v112, v112, v113
	s_nop 2
	v_cvt_pk_bf16_f32 v113, v114, v115
	s_nop 2
	v_cvt_pk_bf16_f32 v114, v104, v105
	v_or_b32_e32 v104, 16, v152
	v_ashrrev_i32_e32 v105, 31, v104
	v_lshlrev_b64 v[104:105], 13, v[104:105]
	v_lshl_add_u64 v[104:105], s[6:7], 0, v[104:105]
	s_nop 2
	v_cvt_pk_bf16_f32 v115, v106, v107
	global_store_dwordx4 v[144:145], v[112:115], off offset:256
	s_mov_b32 s13, 0x100000
	s_mov_b64 s[34:35], 0x100000
	v_lshl_add_u64 v[112:113], v[104:105], 0, v[156:157]
	s_nop 2
	v_cvt_pk_bf16_f32 v104, v116, v117
	s_nop 2
	v_cvt_pk_bf16_f32 v105, v118, v119
	v_cvt_pk_bf16_f32 v106, v108, v109
	v_cvt_pk_bf16_f32 v107, v110, v111
	global_store_dwordx4 v[112:113], v[104:107], off
	v_cvt_pk_bf16_f32 v96, v96, v97
	v_cvt_pk_bf16_f32 v97, v98, v99
	v_cvt_pk_bf16_f32 v98, v88, v89
	v_or_b32_e32 v88, 32, v152
	v_ashrrev_i32_e32 v89, 31, v88
	v_lshlrev_b64 v[88:89], 13, v[88:89]
	v_lshl_add_u64 v[88:89], s[6:7], 0, v[88:89]
	v_cvt_pk_bf16_f32 v99, v90, v91
	global_store_dwordx4 v[112:113], v[96:99], off offset:256
	s_nop 1
	v_lshl_add_u64 v[96:97], v[88:89], 0, v[156:157]
	v_cvt_pk_bf16_f32 v88, v100, v101
	v_cvt_pk_bf16_f32 v89, v102, v103
	v_cvt_pk_bf16_f32 v90, v92, v93
	v_cvt_pk_bf16_f32 v91, v94, v95
	global_store_dwordx4 v[96:97], v[88:91], off
	v_cvt_pk_bf16_f32 v80, v80, v81
	v_cvt_pk_bf16_f32 v81, v82, v83
	v_cvt_pk_bf16_f32 v82, v72, v73
	v_or_b32_e32 v72, 48, v152
	v_ashrrev_i32_e32 v73, 31, v72
	v_lshlrev_b64 v[72:73], 13, v[72:73]
	v_lshl_add_u64 v[72:73], s[6:7], 0, v[72:73]
	v_cvt_pk_bf16_f32 v83, v74, v75
	global_store_dwordx4 v[96:97], v[80:83], off offset:256
	s_nop 1
	v_lshl_add_u64 v[80:81], v[72:73], 0, v[156:157]
	v_cvt_pk_bf16_f32 v72, v84, v85
	v_cvt_pk_bf16_f32 v73, v86, v87
	v_cvt_pk_bf16_f32 v74, v76, v77
	v_cvt_pk_bf16_f32 v75, v78, v79
	global_store_dwordx4 v[80:81], v[72:75], off
	v_cvt_pk_bf16_f32 v68, v68, v69
	v_cvt_pk_bf16_f32 v69, v70, v71
	v_cvt_pk_bf16_f32 v70, v64, v65
	v_cvt_pk_bf16_f32 v71, v66, v67
	global_store_dwordx4 v[80:81], v[68:71], off offset:256
	v_cvt_pk_bf16_f32 v60, v60, v61
	v_cvt_pk_bf16_f32 v61, v62, v63
	v_cvt_pk_bf16_f32 v62, v56, v57
	v_add_co_u32_e32 v56, vcc, s13, v144
	v_lshl_add_u64 v[64:65], v[144:145], 0, s[34:35]
	s_nop 0
	v_addc_co_u32_e32 v57, vcc, 0, v145, vcc
	s_mov_b32 s13, 0x120000
	v_cvt_pk_bf16_f32 v63, v58, v59
	global_store_dwordx4 v[56:57], v[60:63], off
	v_cvt_pk_bf16_f32 v48, v48, v49
	v_cvt_pk_bf16_f32 v49, v50, v51
	v_cvt_pk_bf16_f32 v50, v40, v41
	v_cvt_pk_bf16_f32 v51, v42, v43
	global_store_dwordx4 v[64:65], v[48:51], off offset:256
	s_mov_b64 s[34:35], 0x120000
	v_cvt_pk_bf16_f32 v40, v52, v53
	v_cvt_pk_bf16_f32 v41, v54, v55
	v_cvt_pk_bf16_f32 v42, v44, v45
	v_add_co_u32_e32 v44, vcc, s13, v144
	v_lshl_add_u64 v[48:49], v[144:145], 0, s[34:35]
	s_nop 0
	v_addc_co_u32_e32 v45, vcc, 0, v145, vcc
	s_mov_b32 s13, 0x140000
	v_cvt_pk_bf16_f32 v43, v46, v47
	global_store_dwordx4 v[44:45], v[40:43], off
	v_cvt_pk_bf16_f32 v32, v32, v33
	v_cvt_pk_bf16_f32 v33, v34, v35
	v_cvt_pk_bf16_f32 v34, v24, v25
	v_cvt_pk_bf16_f32 v35, v26, v27
	global_store_dwordx4 v[48:49], v[32:35], off offset:256
	s_mov_b64 s[34:35], 0x140000
	v_cvt_pk_bf16_f32 v24, v36, v37
	v_cvt_pk_bf16_f32 v25, v38, v39
	v_cvt_pk_bf16_f32 v26, v28, v29
	v_add_co_u32_e32 v28, vcc, s13, v144
	v_lshl_add_u64 v[32:33], v[144:145], 0, s[34:35]
	s_nop 0
	v_addc_co_u32_e32 v29, vcc, 0, v145, vcc
	s_mov_b32 s13, 0x160000
	v_cvt_pk_bf16_f32 v27, v30, v31
	global_store_dwordx4 v[28:29], v[24:27], off
	v_cvt_pk_bf16_f32 v16, v16, v17
	v_cvt_pk_bf16_f32 v17, v18, v19
	v_cvt_pk_bf16_f32 v18, v8, v9
	v_cvt_pk_bf16_f32 v19, v10, v11
	global_store_dwordx4 v[32:33], v[16:19], off offset:256
	v_cvt_pk_bf16_f32 v8, v20, v21
	v_cvt_pk_bf16_f32 v9, v22, v23
	v_cvt_pk_bf16_f32 v10, v12, v13
	v_add_co_u32_e32 v12, vcc, s13, v144
	s_mov_b64 s[34:35], 0x160000
	s_nop 0
	v_addc_co_u32_e32 v13, vcc, 0, v145, vcc
	v_lshl_add_u64 v[16:17], v[144:145], 0, s[34:35]
	s_andn2_b64 vcc, exec, s[0:1]
	s_mov_b64 s[0:1], -1
	v_cvt_pk_bf16_f32 v11, v14, v15
	global_store_dwordx4 v[12:13], v[8:11], off
	v_cvt_pk_bf16_f32 v4, v4, v5
	v_cvt_pk_bf16_f32 v5, v6, v7
	v_cvt_pk_bf16_f32 v6, v0, v1
	v_cvt_pk_bf16_f32 v7, v2, v3
	global_store_dwordx4 v[16:17], v[4:7], off offset:256
	s_cbranch_vccnz .LBB0_592
	s_andn2_b64 vcc, exec, s[4:5]
	s_cbranch_vccnz .LBB0_591
	s_barrier
	s_branch .LBB0_591

.LBB0_678:
	s_ashr_i32 s19, s18, 31
	s_lshl_b64 s[34:35], s[18:19], 21
	s_add_u32 s44, s86, s34
	s_addc_u32 s45, s87, s35
	s_and_b64 s[34:35], s[0:1], exec
	s_cselect_b32 s19, s45, s51
	s_cselect_b32 s66, s44, s50
	s_ashr_i32 s17, s16, 31
	s_lshl_b64 s[34:35], s[16:17], 21
	s_add_u32 s46, s88, s34
	s_addc_u32 s47, s90, s35
	s_and_b64 s[34:35], s[0:1], exec
	s_cselect_b32 s17, s47, s53
	s_cselect_b32 s67, s46, s52
	s_add_u32 s50, s50, 0x100080
	s_addc_u32 s51, s51, 0
	s_add_u32 s34, s52, 0x100
	v_mov_b32_e32 v0, 0
	s_addc_u32 s35, s53, 0
	s_mov_b32 s36, -2
	v_mov_b32_e32 v1, v0
	v_mov_b64_e32 v[2:3], 0
	v_mov_b64_e32 v[4:5], 0
	v_mov_b64_e32 v[6:7], 0
	v_mov_b64_e32 v[8:9], 0
	v_mov_b64_e32 v[10:11], 0
	v_mov_b64_e32 v[12:13], 0
	v_mov_b64_e32 v[14:15], 0
	v_mov_b64_e32 v[16:17], 0
	v_mov_b64_e32 v[18:19], 0
	v_mov_b64_e32 v[20:21], 0
	v_mov_b64_e32 v[22:23], 0
	v_mov_b64_e32 v[24:25], 0
	v_mov_b64_e32 v[26:27], 0
	v_mov_b64_e32 v[28:29], 0
	v_mov_b64_e32 v[30:31], 0
	v_mov_b64_e32 v[32:33], 0
	v_mov_b64_e32 v[34:35], 0
	v_mov_b64_e32 v[36:37], 0
	v_mov_b64_e32 v[38:39], 0
	v_mov_b64_e32 v[40:41], 0
	v_mov_b64_e32 v[42:43], 0
	v_mov_b64_e32 v[44:45], 0
	v_mov_b64_e32 v[46:47], 0
	v_mov_b64_e32 v[48:49], 0
	v_mov_b64_e32 v[50:51], 0
	v_mov_b64_e32 v[52:53], 0
	v_mov_b64_e32 v[54:55], 0
	v_mov_b64_e32 v[56:57], 0
	v_mov_b64_e32 v[58:59], 0
	v_mov_b64_e32 v[60:61], 0
	v_mov_b64_e32 v[62:63], 0
	v_mov_b64_e32 v[64:65], 0
	v_mov_b64_e32 v[66:67], 0
	v_mov_b64_e32 v[68:69], 0
	v_mov_b64_e32 v[70:71], 0
	v_mov_b64_e32 v[72:73], 0
	v_mov_b64_e32 v[74:75], 0
	v_mov_b64_e32 v[76:77], 0
	v_mov_b64_e32 v[78:79], 0
	v_mov_b64_e32 v[80:81], 0
	v_mov_b64_e32 v[82:83], 0
	v_mov_b64_e32 v[84:85], 0
	v_mov_b64_e32 v[86:87], 0
	v_mov_b64_e32 v[88:89], 0
	v_mov_b64_e32 v[90:91], 0
	v_mov_b64_e32 v[92:93], 0
	v_mov_b64_e32 v[94:95], 0
	v_mov_b64_e32 v[96:97], 0
	v_mov_b64_e32 v[98:99], 0
	v_mov_b64_e32 v[100:101], 0
	v_mov_b64_e32 v[102:103], 0
	v_mov_b64_e32 v[104:105], 0
	v_mov_b64_e32 v[106:107], 0
	v_mov_b64_e32 v[108:109], 0
	v_mov_b64_e32 v[110:111], 0
	v_mov_b64_e32 v[112:113], 0
	v_mov_b64_e32 v[114:115], 0
	v_mov_b64_e32 v[116:117], 0
	v_mov_b64_e32 v[118:119], 0
	v_mov_b64_e32 v[120:121], 0
	v_mov_b64_e32 v[122:123], 0
	v_mov_b64_e32 v[124:125], 0
	v_mov_b64_e32 v[126:127], 0
	s_waitcnt vmcnt(0)
	s_cmpk_lt_u32 s97, 0x100
	s_cbranch_scc1 .Lmy_prio_skip3
	s_setprio 1

.LBB0_757:
	s_ashr_i32 s13, s12, 31
	s_lshl_b64 s[16:17], s[12:13], 21
	s_add_u32 s16, s33, s16
	s_addc_u32 s17, s66, s17
	s_and_b64 s[18:19], s[0:1], exec
	s_cselect_b32 s13, s17, s49
	s_cselect_b32 s64, s16, s48
	s_ashr_i32 s11, s10, 31
	s_lshl_b64 s[18:19], s[10:11], 21
	s_add_u32 s18, s91, s18
	s_addc_u32 s19, s85, s19
	s_and_b64 s[34:35], s[0:1], exec
	s_cselect_b32 s11, s19, s47
	s_cselect_b32 s65, s18, s46
	s_add_u32 s38, s48, 0x100080
	s_addc_u32 s39, s49, 0
	s_add_u32 s34, s46, 0x100
	v_mov_b32_e32 v0, 0
	s_addc_u32 s35, s47, 0
	s_mov_b32 s36, -2
	v_mov_b32_e32 v1, v0
	v_mov_b64_e32 v[2:3], 0
	v_mov_b64_e32 v[4:5], 0
	v_mov_b64_e32 v[6:7], 0
	v_mov_b64_e32 v[8:9], 0
	v_mov_b64_e32 v[10:11], 0
	v_mov_b64_e32 v[12:13], 0
	v_mov_b64_e32 v[14:15], 0
	v_mov_b64_e32 v[16:17], 0
	v_mov_b64_e32 v[18:19], 0
	v_mov_b64_e32 v[20:21], 0
	v_mov_b64_e32 v[22:23], 0
	v_mov_b64_e32 v[24:25], 0
	v_mov_b64_e32 v[26:27], 0
	v_mov_b64_e32 v[28:29], 0
	v_mov_b64_e32 v[30:31], 0
	v_mov_b64_e32 v[32:33], 0
	v_mov_b64_e32 v[34:35], 0
	v_mov_b64_e32 v[36:37], 0
	v_mov_b64_e32 v[38:39], 0
	v_mov_b64_e32 v[40:41], 0
	v_mov_b64_e32 v[42:43], 0
	v_mov_b64_e32 v[44:45], 0
	v_mov_b64_e32 v[46:47], 0
	v_mov_b64_e32 v[48:49], 0
	v_mov_b64_e32 v[50:51], 0
	v_mov_b64_e32 v[52:53], 0
	v_mov_b64_e32 v[54:55], 0
	v_mov_b64_e32 v[56:57], 0
	v_mov_b64_e32 v[58:59], 0
	v_mov_b64_e32 v[60:61], 0
	v_mov_b64_e32 v[62:63], 0
	v_mov_b64_e32 v[64:65], 0
	v_mov_b64_e32 v[66:67], 0
	v_mov_b64_e32 v[68:69], 0
	v_mov_b64_e32 v[70:71], 0
	v_mov_b64_e32 v[72:73], 0
	v_mov_b64_e32 v[74:75], 0
	v_mov_b64_e32 v[76:77], 0
	v_mov_b64_e32 v[78:79], 0
	v_mov_b64_e32 v[80:81], 0
	v_mov_b64_e32 v[82:83], 0
	v_mov_b64_e32 v[84:85], 0
	v_mov_b64_e32 v[86:87], 0
	v_mov_b64_e32 v[88:89], 0
	v_mov_b64_e32 v[90:91], 0
	v_mov_b64_e32 v[92:93], 0
	v_mov_b64_e32 v[94:95], 0
	v_mov_b64_e32 v[96:97], 0
	v_mov_b64_e32 v[98:99], 0
	v_mov_b64_e32 v[100:101], 0
	v_mov_b64_e32 v[102:103], 0
	v_mov_b64_e32 v[104:105], 0
	v_mov_b64_e32 v[106:107], 0
	v_mov_b64_e32 v[108:109], 0
	v_mov_b64_e32 v[110:111], 0
	v_mov_b64_e32 v[112:113], 0
	v_mov_b64_e32 v[114:115], 0
	v_mov_b64_e32 v[116:117], 0
	v_mov_b64_e32 v[118:119], 0
	v_mov_b64_e32 v[120:121], 0
	v_mov_b64_e32 v[122:123], 0
	v_mov_b64_e32 v[124:125], 0
	v_mov_b64_e32 v[126:127], 0
	s_waitcnt vmcnt(0)
	s_cmpk_lt_u32 s97, 0x100
	s_cbranch_scc1 .Lmy_prio_skip4
	s_setprio 1

.LBB0_761:
	v_lshl_add_u32 v148, s44, 8, v150
	v_lshl_or_b32 v146, s63, 8, v152
	s_cmp_lt_i32 s44, 64
	v_readlane_b32 s36, v254, 7
	v_ashrrev_i32_e32 v149, 31, v148
	v_readlane_b32 s37, v254, 8
	v_readlane_b32 s38, v254, 9
	v_readlane_b32 s39, v254, 10
	v_ashrrev_i32_e32 v147, 31, v146
	v_lshlrev_b64 v[144:145], 12, v[148:149]
	s_cselect_b32 s39, s37, s60
	s_cselect_b32 s38, s36, s59
	v_lshl_add_u64 v[144:145], v[144:145], 0, v[146:147]
	v_lshl_add_u64 v[164:165], v[144:145], 2, s[38:39]
	global_load_dwordx4 v[156:159], v[164:165], off
	global_load_dwordx4 v[160:163], v[164:165], off offset:16
	v_lshl_add_u64 v[166:167], v[144:145], 1, s[74:75]
	s_mov_b64 s[34:35], 0x80000
	s_andn2_b64 vcc, exec, s[0:1]
	s_mov_b64 s[0:1], -1
	v_readlane_b32 s40, v254, 11
	v_readlane_b32 s41, v254, 12
	v_readlane_b32 s42, v254, 13
	v_readlane_b32 s43, v254, 14
	v_readlane_b32 s44, v254, 15
	v_readlane_b32 s45, v254, 16
	v_readlane_b32 s46, v254, 17
	v_readlane_b32 s47, v254, 18
	v_readlane_b32 s48, v254, 19
	v_readlane_b32 s49, v254, 20
	v_readlane_b32 s50, v254, 21
	v_readlane_b32 s51, v254, 22
	s_waitcnt vmcnt(0)
	v_pk_add_f32 v[124:125], v[124:125], v[156:157]
	v_pk_add_f32 v[156:157], v[122:123], v[162:163]
	v_pk_add_f32 v[122:123], v[120:121], v[160:161]
	v_pk_add_f32 v[126:127], v[126:127], v[158:159]
	s_nop 2
	v_cvt_pk_bf16_f32 v120, v124, v125
	s_nop 0
	s_nop 2
	v_cvt_pk_bf16_f32 v121, v126, v127
	s_nop 2
	v_cvt_pk_bf16_f32 v122, v122, v123
	s_nop 2
	v_cvt_pk_bf16_f32 v123, v156, v157
	global_store_dwordx4 v[166:167], v[120:123], off
	global_load_dwordx4 v[120:123], v[164:165], off offset:512
	s_nop 0
	global_load_dwordx4 v[124:127], v[164:165], off offset:528
	v_or_b32_e32 v156, 16, v148
	v_ashrrev_i32_e32 v157, 31, v156
	v_lshlrev_b64 v[156:157], 12, v[156:157]
	v_lshl_add_u64 v[156:157], v[156:157], 0, v[146:147]
	v_lshl_add_u64 v[158:159], v[156:157], 2, s[38:39]
	s_waitcnt vmcnt(1)
	v_pk_add_f32 v[116:117], v[116:117], v[120:121]
	s_waitcnt vmcnt(0)
	v_pk_add_f32 v[120:121], v[114:115], v[126:127]
	v_pk_add_f32 v[114:115], v[112:113], v[124:125]
	v_pk_add_f32 v[118:119], v[118:119], v[122:123]
	s_nop 2
	v_cvt_pk_bf16_f32 v112, v116, v117
	s_nop 0
	s_nop 2
	v_cvt_pk_bf16_f32 v113, v118, v119
	s_nop 2
	v_cvt_pk_bf16_f32 v114, v114, v115
	s_nop 2
	v_cvt_pk_bf16_f32 v115, v120, v121
	global_store_dwordx4 v[166:167], v[112:115], off offset:256
	global_load_dwordx4 v[112:115], v[158:159], off
	s_nop 0
	global_load_dwordx4 v[116:119], v[158:159], off offset:16
	v_lshl_add_u64 v[120:121], v[156:157], 1, s[74:75]
	s_waitcnt vmcnt(1)
	v_pk_add_f32 v[108:109], v[108:109], v[112:113]
	s_waitcnt vmcnt(0)
	v_pk_add_f32 v[112:113], v[106:107], v[118:119]
	v_pk_add_f32 v[106:107], v[104:105], v[116:117]
	v_pk_add_f32 v[110:111], v[110:111], v[114:115]
	s_nop 2
	v_cvt_pk_bf16_f32 v104, v108, v109
	s_nop 0
	s_nop 2
	v_cvt_pk_bf16_f32 v105, v110, v111
	s_nop 2
	v_cvt_pk_bf16_f32 v106, v106, v107
	v_cvt_pk_bf16_f32 v107, v112, v113
	global_store_dwordx4 v[120:121], v[104:107], off
	global_load_dwordx4 v[104:107], v[158:159], off offset:512
	s_nop 0
	global_load_dwordx4 v[108:111], v[158:159], off offset:528
	v_or_b32_e32 v112, 32, v148
	v_ashrrev_i32_e32 v113, 31, v112
	v_lshlrev_b64 v[112:113], 12, v[112:113]
	v_lshl_add_u64 v[112:113], v[112:113], 0, v[146:147]
	v_lshl_add_u64 v[114:115], v[112:113], 2, s[38:39]
	s_waitcnt vmcnt(1)
	v_pk_add_f32 v[100:101], v[100:101], v[104:105]
	s_waitcnt vmcnt(0)
	v_pk_add_f32 v[104:105], v[98:99], v[110:111]
	v_pk_add_f32 v[98:99], v[96:97], v[108:109]
	v_pk_add_f32 v[102:103], v[102:103], v[106:107]
	v_cvt_pk_bf16_f32 v96, v100, v101
	s_nop 0
	v_cvt_pk_bf16_f32 v97, v102, v103
	v_cvt_pk_bf16_f32 v98, v98, v99
	v_cvt_pk_bf16_f32 v99, v104, v105
	global_store_dwordx4 v[120:121], v[96:99], off offset:256
	global_load_dwordx4 v[96:99], v[114:115], off
	s_nop 0
	global_load_dwordx4 v[100:103], v[114:115], off offset:16
	v_lshl_add_u64 v[104:105], v[112:113], 1, s[74:75]
	s_waitcnt vmcnt(1)
	v_pk_add_f32 v[92:93], v[92:93], v[96:97]
	s_waitcnt vmcnt(0)
	v_pk_add_f32 v[96:97], v[90:91], v[102:103]
	v_pk_add_f32 v[90:91], v[88:89], v[100:101]
	v_pk_add_f32 v[94:95], v[94:95], v[98:99]
	v_cvt_pk_bf16_f32 v88, v92, v93
	s_nop 0
	v_cvt_pk_bf16_f32 v89, v94, v95
	v_cvt_pk_bf16_f32 v90, v90, v91
	v_cvt_pk_bf16_f32 v91, v96, v97
	global_store_dwordx4 v[104:105], v[88:91], off
	global_load_dwordx4 v[88:91], v[114:115], off offset:512
	s_nop 0
	global_load_dwordx4 v[92:95], v[114:115], off offset:528
	v_or_b32_e32 v96, 48, v148
	v_ashrrev_i32_e32 v97, 31, v96
	v_lshlrev_b64 v[96:97], 12, v[96:97]
	v_lshl_add_u64 v[96:97], v[96:97], 0, v[146:147]
	v_lshl_add_u64 v[98:99], v[96:97], 2, s[38:39]
	s_waitcnt vmcnt(1)
	v_pk_add_f32 v[84:85], v[84:85], v[88:89]
	s_waitcnt vmcnt(0)
	v_pk_add_f32 v[88:89], v[82:83], v[94:95]
	v_pk_add_f32 v[82:83], v[80:81], v[92:93]
	v_pk_add_f32 v[86:87], v[86:87], v[90:91]
	v_cvt_pk_bf16_f32 v80, v84, v85
	s_nop 0
	v_cvt_pk_bf16_f32 v81, v86, v87
	v_cvt_pk_bf16_f32 v82, v82, v83
	v_cvt_pk_bf16_f32 v83, v88, v89
	global_store_dwordx4 v[104:105], v[80:83], off offset:256
	global_load_dwordx4 v[80:83], v[98:99], off
	s_nop 0
	global_load_dwordx4 v[84:87], v[98:99], off offset:16
	v_lshl_add_u64 v[88:89], v[96:97], 1, s[74:75]
	s_waitcnt vmcnt(1)
	v_pk_add_f32 v[76:77], v[76:77], v[80:81]
	s_waitcnt vmcnt(0)
	v_pk_add_f32 v[80:81], v[74:75], v[86:87]
	v_pk_add_f32 v[74:75], v[72:73], v[84:85]
	v_pk_add_f32 v[78:79], v[78:79], v[82:83]
	v_cvt_pk_bf16_f32 v72, v76, v77
	s_nop 0
	v_cvt_pk_bf16_f32 v73, v78, v79
	v_cvt_pk_bf16_f32 v74, v74, v75
	v_cvt_pk_bf16_f32 v75, v80, v81
	global_store_dwordx4 v[88:89], v[72:75], off
	global_load_dwordx4 v[72:75], v[98:99], off offset:512
	s_nop 0
	global_load_dwordx4 v[76:79], v[98:99], off offset:528
	v_lshl_add_u64 v[80:81], v[144:145], 0, s[34:35]
	v_lshl_add_u64 v[82:83], v[80:81], 2, s[38:39]
	s_mov_b64 s[34:35], 0x90000
	s_waitcnt vmcnt(1)
	v_pk_add_f32 v[68:69], v[68:69], v[72:73]
	s_waitcnt vmcnt(0)
	v_pk_add_f32 v[72:73], v[66:67], v[78:79]
	v_pk_add_f32 v[66:67], v[64:65], v[76:77]
	v_pk_add_f32 v[70:71], v[70:71], v[74:75]
	v_cvt_pk_bf16_f32 v64, v68, v69
	s_nop 0
	v_cvt_pk_bf16_f32 v65, v70, v71
	v_cvt_pk_bf16_f32 v66, v66, v67
	v_cvt_pk_bf16_f32 v67, v72, v73
	global_store_dwordx4 v[88:89], v[64:67], off offset:256
	global_load_dwordx4 v[64:67], v[82:83], off
	s_nop 0
	global_load_dwordx4 v[68:71], v[82:83], off offset:16
	v_lshl_add_u64 v[72:73], v[80:81], 1, s[74:75]
	s_waitcnt vmcnt(1)
	v_pk_add_f32 v[60:61], v[60:61], v[64:65]
	s_waitcnt vmcnt(0)
	v_pk_add_f32 v[64:65], v[58:59], v[70:71]
	v_pk_add_f32 v[58:59], v[56:57], v[68:69]
	v_pk_add_f32 v[62:63], v[62:63], v[66:67]
	v_cvt_pk_bf16_f32 v56, v60, v61
	s_nop 0
	v_cvt_pk_bf16_f32 v57, v62, v63
	v_cvt_pk_bf16_f32 v58, v58, v59
	v_cvt_pk_bf16_f32 v59, v64, v65
	global_store_dwordx4 v[72:73], v[56:59], off
	global_load_dwordx4 v[56:59], v[82:83], off offset:512
	s_nop 0
	global_load_dwordx4 v[60:63], v[82:83], off offset:528
	v_lshl_add_u64 v[64:65], v[144:145], 0, s[34:35]
	v_lshl_add_u64 v[66:67], v[64:65], 2, s[38:39]
	s_mov_b64 s[34:35], 0xa0000
	s_waitcnt vmcnt(1)
	v_pk_add_f32 v[52:53], v[52:53], v[56:57]
	s_waitcnt vmcnt(0)
	v_pk_add_f32 v[56:57], v[50:51], v[62:63]
	v_pk_add_f32 v[50:51], v[48:49], v[60:61]
	v_pk_add_f32 v[54:55], v[54:55], v[58:59]
	v_cvt_pk_bf16_f32 v48, v52, v53
	s_nop 0
	v_cvt_pk_bf16_f32 v49, v54, v55
	v_cvt_pk_bf16_f32 v50, v50, v51
	v_cvt_pk_bf16_f32 v51, v56, v57
	global_store_dwordx4 v[72:73], v[48:51], off offset:256
	global_load_dwordx4 v[48:51], v[66:67], off
	s_nop 0
	global_load_dwordx4 v[52:55], v[66:67], off offset:16
	v_lshl_add_u64 v[56:57], v[64:65], 1, s[74:75]
	s_waitcnt vmcnt(1)
	v_pk_add_f32 v[44:45], v[44:45], v[48:49]
	s_waitcnt vmcnt(0)
	v_pk_add_f32 v[48:49], v[42:43], v[54:55]
	v_pk_add_f32 v[42:43], v[40:41], v[52:53]
	v_pk_add_f32 v[46:47], v[46:47], v[50:51]
	v_cvt_pk_bf16_f32 v40, v44, v45
	s_nop 0
	v_cvt_pk_bf16_f32 v41, v46, v47
	v_cvt_pk_bf16_f32 v42, v42, v43
	v_cvt_pk_bf16_f32 v43, v48, v49
	global_store_dwordx4 v[56:57], v[40:43], off
	global_load_dwordx4 v[40:43], v[66:67], off offset:512
	s_nop 0
	global_load_dwordx4 v[44:47], v[66:67], off offset:528
	v_lshl_add_u64 v[48:49], v[144:145], 0, s[34:35]
	v_lshl_add_u64 v[50:51], v[48:49], 2, s[38:39]
	s_mov_b64 s[34:35], 0xb0000
	s_waitcnt vmcnt(1)
	v_pk_add_f32 v[36:37], v[36:37], v[40:41]
	s_waitcnt vmcnt(0)
	v_pk_add_f32 v[40:41], v[34:35], v[46:47]
	v_pk_add_f32 v[34:35], v[32:33], v[44:45]
	v_pk_add_f32 v[38:39], v[38:39], v[42:43]
	v_cvt_pk_bf16_f32 v32, v36, v37
	s_nop 0
	v_cvt_pk_bf16_f32 v33, v38, v39
	v_cvt_pk_bf16_f32 v34, v34, v35
	v_cvt_pk_bf16_f32 v35, v40, v41
	global_store_dwordx4 v[56:57], v[32:35], off offset:256
	global_load_dwordx4 v[32:35], v[50:51], off
	s_nop 0
	global_load_dwordx4 v[36:39], v[50:51], off offset:16
	v_lshl_add_u64 v[40:41], v[48:49], 1, s[74:75]
	s_waitcnt vmcnt(1)
	v_pk_add_f32 v[28:29], v[28:29], v[32:33]
	s_waitcnt vmcnt(0)
	v_pk_add_f32 v[32:33], v[26:27], v[38:39]
	v_pk_add_f32 v[26:27], v[24:25], v[36:37]
	v_pk_add_f32 v[30:31], v[30:31], v[34:35]
	v_cvt_pk_bf16_f32 v24, v28, v29
	s_nop 0
	v_cvt_pk_bf16_f32 v25, v30, v31
	v_cvt_pk_bf16_f32 v26, v26, v27
	v_cvt_pk_bf16_f32 v27, v32, v33
	global_store_dwordx4 v[40:41], v[24:27], off
	global_load_dwordx4 v[24:27], v[50:51], off offset:512
	s_nop 0
	global_load_dwordx4 v[28:31], v[50:51], off offset:528
	v_lshl_add_u64 v[32:33], v[144:145], 0, s[34:35]
	v_lshl_add_u64 v[34:35], v[32:33], 2, s[38:39]
	s_waitcnt vmcnt(1)
	v_pk_add_f32 v[20:21], v[20:21], v[24:25]
	s_waitcnt vmcnt(0)
	v_pk_add_f32 v[24:25], v[18:19], v[30:31]
	v_pk_add_f32 v[18:19], v[16:17], v[28:29]
	v_pk_add_f32 v[22:23], v[22:23], v[26:27]
	v_cvt_pk_bf16_f32 v16, v20, v21
	s_nop 0
	v_cvt_pk_bf16_f32 v17, v22, v23
	v_cvt_pk_bf16_f32 v18, v18, v19
	v_cvt_pk_bf16_f32 v19, v24, v25
	global_store_dwordx4 v[40:41], v[16:19], off offset:256
	global_load_dwordx4 v[16:19], v[34:35], off
	s_nop 0
	global_load_dwordx4 v[20:23], v[34:35], off offset:16
	v_lshl_add_u64 v[24:25], v[32:33], 1, s[74:75]
	s_waitcnt vmcnt(1)
	v_pk_add_f32 v[12:13], v[12:13], v[16:17]
	s_waitcnt vmcnt(0)
	v_pk_add_f32 v[16:17], v[10:11], v[22:23]
	v_pk_add_f32 v[10:11], v[8:9], v[20:21]
	v_pk_add_f32 v[14:15], v[14:15], v[18:19]
	v_cvt_pk_bf16_f32 v8, v12, v13
	s_nop 0
	v_cvt_pk_bf16_f32 v9, v14, v15
	v_cvt_pk_bf16_f32 v10, v10, v11
	v_cvt_pk_bf16_f32 v11, v16, v17
	global_store_dwordx4 v[24:25], v[8:11], off
	global_load_dwordx4 v[8:11], v[34:35], off offset:512
	s_nop 0
	global_load_dwordx4 v[12:15], v[34:35], off offset:528
	s_waitcnt vmcnt(1)
	v_pk_add_f32 v[4:5], v[4:5], v[8:9]
	s_waitcnt vmcnt(0)
	v_pk_add_f32 v[8:9], v[2:3], v[14:15]
	v_pk_add_f32 v[2:3], v[0:1], v[12:13]
	v_pk_add_f32 v[6:7], v[6:7], v[10:11]
	v_cvt_pk_bf16_f32 v0, v4, v5
	s_nop 0
	v_cvt_pk_bf16_f32 v1, v6, v7
	v_cvt_pk_bf16_f32 v2, v2, v3
	v_cvt_pk_bf16_f32 v3, v8, v9
	global_store_dwordx4 v[24:25], v[0:3], off offset:256
	s_cbranch_vccnz .LBB0_750
	s_andn2_b64 vcc, exec, s[4:5]
	s_cbranch_vccnz .LBB0_749
	s_barrier
	s_branch .LBB0_749

.LBB0_913:
	s_ashr_i32 s41, s40, 31
	s_lshl_b64 s[34:35], s[40:41], 21
	v_cmp_lt_i64_e32 vcc, s[42:43], v[174:175]
	s_add_u32 s42, s86, s34
	s_addc_u32 s43, s87, s35
	s_and_b64 s[34:35], vcc, exec
	s_cselect_b32 s41, s43, s51
	s_cselect_b32 s47, s42, s50
	s_ashr_i32 s39, s38, 31
	s_lshl_b64 s[34:35], s[38:39], 21
	s_add_u32 s44, s54, s34
	s_addc_u32 s45, s64, s35
	s_and_b64 s[34:35], vcc, exec
	s_cselect_b32 s39, s45, s53
	s_cselect_b32 s34, s44, s52
	s_add_u32 s35, s52, 0x100
	v_mov_b32_e32 v0, 0
	s_mov_b32 s16, s54
	s_addc_u32 s49, s53, 0
	s_mov_b32 s96, -2
	v_mov_b32_e32 v1, v0
	v_mov_b64_e32 v[2:3], 0
	v_mov_b64_e32 v[4:5], 0
	v_mov_b64_e32 v[6:7], 0
	v_mov_b64_e32 v[8:9], 0
	v_mov_b64_e32 v[10:11], 0
	v_mov_b64_e32 v[12:13], 0
	v_mov_b64_e32 v[14:15], 0
	v_mov_b64_e32 v[16:17], 0
	v_mov_b64_e32 v[18:19], 0
	v_mov_b64_e32 v[20:21], 0
	v_mov_b64_e32 v[22:23], 0
	v_mov_b64_e32 v[24:25], 0
	v_mov_b64_e32 v[26:27], 0
	v_mov_b64_e32 v[28:29], 0
	v_mov_b64_e32 v[30:31], 0
	v_mov_b64_e32 v[32:33], 0
	v_mov_b64_e32 v[34:35], 0
	v_mov_b64_e32 v[36:37], 0
	v_mov_b64_e32 v[38:39], 0
	v_mov_b64_e32 v[40:41], 0
	v_mov_b64_e32 v[42:43], 0
	v_mov_b64_e32 v[44:45], 0
	v_mov_b64_e32 v[46:47], 0
	v_mov_b64_e32 v[48:49], 0
	v_mov_b64_e32 v[50:51], 0
	v_mov_b64_e32 v[52:53], 0
	v_mov_b64_e32 v[54:55], 0
	v_mov_b64_e32 v[56:57], 0
	v_mov_b64_e32 v[58:59], 0
	v_mov_b64_e32 v[60:61], 0
	v_mov_b64_e32 v[62:63], 0
	v_mov_b64_e32 v[64:65], 0
	v_mov_b64_e32 v[66:67], 0
	v_mov_b64_e32 v[68:69], 0
	v_mov_b64_e32 v[70:71], 0
	v_mov_b64_e32 v[72:73], 0
	v_mov_b64_e32 v[74:75], 0
	v_mov_b64_e32 v[76:77], 0
	v_mov_b64_e32 v[78:79], 0
	v_mov_b64_e32 v[80:81], 0
	v_mov_b64_e32 v[82:83], 0
	v_mov_b64_e32 v[84:85], 0
	v_mov_b64_e32 v[86:87], 0
	v_mov_b64_e32 v[88:89], 0
	v_mov_b64_e32 v[90:91], 0
	v_mov_b64_e32 v[92:93], 0
	v_mov_b64_e32 v[94:95], 0
	v_mov_b64_e32 v[96:97], 0
	v_mov_b64_e32 v[98:99], 0
	v_mov_b64_e32 v[100:101], 0
	v_mov_b64_e32 v[102:103], 0
	v_mov_b64_e32 v[104:105], 0
	v_mov_b64_e32 v[106:107], 0
	v_mov_b64_e32 v[108:109], 0
	v_mov_b64_e32 v[110:111], 0
	v_mov_b64_e32 v[112:113], 0
	v_mov_b64_e32 v[114:115], 0
	v_mov_b64_e32 v[116:117], 0
	v_mov_b64_e32 v[118:119], 0
	v_mov_b64_e32 v[120:121], 0
	v_mov_b64_e32 v[122:123], 0
	v_mov_b64_e32 v[124:125], 0
	v_mov_b64_e32 v[126:127], 0
	s_cmpk_lt_u32 s97, 0x100
	s_cbranch_scc1 .Lmy_prio_skip5
	s_setprio 1

.LBB0_1076:
	s_add_u32 s34, s28, 0x100
	v_mov_b32_e32 v0, 0
	s_addc_u32 s35, s29, 0
	s_mov_b32 s53, -2
	v_mov_b32_e32 v1, v0
	v_mov_b64_e32 v[2:3], 0
	v_mov_b64_e32 v[4:5], 0
	v_mov_b64_e32 v[6:7], 0
	v_mov_b64_e32 v[8:9], 0
	v_mov_b64_e32 v[10:11], 0
	v_mov_b64_e32 v[12:13], 0
	v_mov_b64_e32 v[14:15], 0
	v_mov_b64_e32 v[16:17], 0
	v_mov_b64_e32 v[18:19], 0
	v_mov_b64_e32 v[20:21], 0
	v_mov_b64_e32 v[22:23], 0
	v_mov_b64_e32 v[24:25], 0
	v_mov_b64_e32 v[26:27], 0
	v_mov_b64_e32 v[28:29], 0
	v_mov_b64_e32 v[30:31], 0
	v_mov_b64_e32 v[32:33], 0
	v_mov_b64_e32 v[34:35], 0
	v_mov_b64_e32 v[36:37], 0
	v_mov_b64_e32 v[38:39], 0
	v_mov_b64_e32 v[40:41], 0
	v_mov_b64_e32 v[42:43], 0
	v_mov_b64_e32 v[44:45], 0
	v_mov_b64_e32 v[46:47], 0
	v_mov_b64_e32 v[48:49], 0
	v_mov_b64_e32 v[50:51], 0
	v_mov_b64_e32 v[52:53], 0
	v_mov_b64_e32 v[54:55], 0
	v_mov_b64_e32 v[56:57], 0
	v_mov_b64_e32 v[58:59], 0
	v_mov_b64_e32 v[60:61], 0
	v_mov_b64_e32 v[62:63], 0
	v_mov_b64_e32 v[64:65], 0
	v_mov_b64_e32 v[66:67], 0
	v_mov_b64_e32 v[68:69], 0
	v_mov_b64_e32 v[70:71], 0
	v_mov_b64_e32 v[72:73], 0
	v_mov_b64_e32 v[74:75], 0
	v_mov_b64_e32 v[76:77], 0
	v_mov_b64_e32 v[78:79], 0
	v_mov_b64_e32 v[80:81], 0
	v_mov_b64_e32 v[82:83], 0
	v_mov_b64_e32 v[84:85], 0
	v_mov_b64_e32 v[86:87], 0
	v_mov_b64_e32 v[88:89], 0
	v_mov_b64_e32 v[90:91], 0
	v_mov_b64_e32 v[92:93], 0
	v_mov_b64_e32 v[94:95], 0
	v_mov_b64_e32 v[96:97], 0
	v_mov_b64_e32 v[98:99], 0
	v_mov_b64_e32 v[100:101], 0
	v_mov_b64_e32 v[102:103], 0
	v_mov_b64_e32 v[104:105], 0
	v_mov_b64_e32 v[106:107], 0
	v_mov_b64_e32 v[108:109], 0
	v_mov_b64_e32 v[110:111], 0
	v_mov_b64_e32 v[112:113], 0
	v_mov_b64_e32 v[114:115], 0
	v_mov_b64_e32 v[116:117], 0
	v_mov_b64_e32 v[118:119], 0
	v_mov_b64_e32 v[120:121], 0
	v_mov_b64_e32 v[122:123], 0
	v_mov_b64_e32 v[124:125], 0
	v_mov_b64_e32 v[126:127], 0
	s_cmpk_lt_u32 s97, 0x100
	s_cbranch_scc1 .Lmy_prio_skip6
	s_setprio 1

.LBB0_1080:
	v_lshl_add_u32 v148, s51, 8, v150
	v_lshl_or_b32 v146, s52, 8, v152
	v_ashrrev_i32_e32 v149, 31, v148
	v_ashrrev_i32_e32 v147, 31, v146
	v_lshlrev_b64 v[144:145], 12, v[148:149]
	v_lshl_add_u64 v[144:145], v[144:145], 0, v[146:147]
	v_lshlrev_b64 v[144:145], 1, v[144:145]
	v_lshl_add_u64 v[160:161], s[74:75], 0, v[144:145]
	global_load_dwordx4 v[156:159], v[160:161], off
	v_lshl_add_u64 v[162:163], s[86:87], 0, v[144:145]
	s_and_b64 vcc, exec, s[0:1]
	s_mov_b64 s[0:1], -1
	s_waitcnt vmcnt(0)
	v_lshlrev_b32_e32 v164, 16, v156
	v_and_b32_e32 v165, 0xffff0000, v156
	v_lshlrev_b32_e32 v156, 16, v157
	v_and_b32_e32 v157, 0xffff0000, v157
	v_lshlrev_b32_e32 v166, 16, v158
	v_and_b32_e32 v167, 0xffff0000, v158
	v_lshlrev_b32_e32 v158, 16, v159
	v_and_b32_e32 v159, 0xffff0000, v159
	v_pk_add_f32 v[126:127], v[126:127], v[156:157]
	v_pk_add_f32 v[156:157], v[122:123], v[158:159]
	v_pk_add_f32 v[122:123], v[120:121], v[166:167]
	v_pk_add_f32 v[124:125], v[124:125], v[164:165]
	s_nop 0
	s_nop 2
	v_cvt_pk_bf16_f32 v120, v124, v125
	s_nop 2
	v_cvt_pk_bf16_f32 v121, v126, v127
	s_nop 2
	v_cvt_pk_bf16_f32 v122, v122, v123
	s_nop 2
	v_cvt_pk_bf16_f32 v123, v156, v157
	global_store_dwordx4 v[162:163], v[120:123], off
	global_load_dwordx4 v[120:123], v[160:161], off offset:256
	v_or_b32_e32 v124, 16, v148
	v_ashrrev_i32_e32 v125, 31, v124
	v_lshlrev_b64 v[124:125], 12, v[124:125]
	v_lshl_add_u64 v[124:125], v[124:125], 0, v[146:147]
	v_lshlrev_b64 v[124:125], 1, v[124:125]
	v_lshl_add_u64 v[126:127], s[74:75], 0, v[124:125]
	s_waitcnt vmcnt(0)
	v_lshlrev_b32_e32 v156, 16, v120
	v_and_b32_e32 v157, 0xffff0000, v120
	v_lshlrev_b32_e32 v120, 16, v121
	v_and_b32_e32 v121, 0xffff0000, v121
	v_lshlrev_b32_e32 v158, 16, v122
	v_and_b32_e32 v159, 0xffff0000, v122
	v_lshlrev_b32_e32 v122, 16, v123
	v_and_b32_e32 v123, 0xffff0000, v123
	v_pk_add_f32 v[118:119], v[118:119], v[120:121]
	v_pk_add_f32 v[120:121], v[114:115], v[122:123]
	v_pk_add_f32 v[114:115], v[112:113], v[158:159]
	v_pk_add_f32 v[116:117], v[116:117], v[156:157]
	s_nop 0
	s_nop 2
	v_cvt_pk_bf16_f32 v112, v116, v117
	s_nop 2
	v_cvt_pk_bf16_f32 v113, v118, v119
	s_nop 2
	v_cvt_pk_bf16_f32 v114, v114, v115
	s_nop 2
	v_cvt_pk_bf16_f32 v115, v120, v121
	global_store_dwordx4 v[162:163], v[112:115], off offset:256
	global_load_dwordx4 v[112:115], v[126:127], off
	v_lshl_add_u64 v[116:117], s[86:87], 0, v[124:125]
	s_waitcnt vmcnt(0)
	v_lshlrev_b32_e32 v118, 16, v112
	v_and_b32_e32 v119, 0xffff0000, v112
	v_lshlrev_b32_e32 v112, 16, v113
	v_and_b32_e32 v113, 0xffff0000, v113
	v_lshlrev_b32_e32 v120, 16, v114
	v_and_b32_e32 v121, 0xffff0000, v114
	v_lshlrev_b32_e32 v114, 16, v115
	v_and_b32_e32 v115, 0xffff0000, v115
	v_pk_add_f32 v[110:111], v[110:111], v[112:113]
	v_pk_add_f32 v[112:113], v[106:107], v[114:115]
	v_pk_add_f32 v[106:107], v[104:105], v[120:121]
	v_pk_add_f32 v[108:109], v[108:109], v[118:119]
	s_nop 0
	s_nop 2
	v_cvt_pk_bf16_f32 v104, v108, v109
	s_nop 2
	v_cvt_pk_bf16_f32 v105, v110, v111
	s_nop 2
	v_cvt_pk_bf16_f32 v106, v106, v107
	s_nop 2
	v_cvt_pk_bf16_f32 v107, v112, v113
	global_store_dwordx4 v[116:117], v[104:107], off
	global_load_dwordx4 v[104:107], v[126:127], off offset:256
	v_or_b32_e32 v108, 32, v148
	v_ashrrev_i32_e32 v109, 31, v108
	v_lshlrev_b64 v[108:109], 12, v[108:109]
	v_lshl_add_u64 v[108:109], v[108:109], 0, v[146:147]
	v_lshlrev_b64 v[108:109], 1, v[108:109]
	v_lshl_add_u64 v[110:111], s[74:75], 0, v[108:109]
	s_waitcnt vmcnt(0)
	v_lshlrev_b32_e32 v112, 16, v104
	v_and_b32_e32 v113, 0xffff0000, v104
	v_lshlrev_b32_e32 v104, 16, v105
	v_and_b32_e32 v105, 0xffff0000, v105
	v_lshlrev_b32_e32 v114, 16, v106
	v_and_b32_e32 v115, 0xffff0000, v106
	v_lshlrev_b32_e32 v106, 16, v107
	v_and_b32_e32 v107, 0xffff0000, v107
	v_pk_add_f32 v[102:103], v[102:103], v[104:105]
	v_pk_add_f32 v[104:105], v[98:99], v[106:107]
	v_pk_add_f32 v[98:99], v[96:97], v[114:115]
	v_pk_add_f32 v[100:101], v[100:101], v[112:113]
	s_nop 0
	s_nop 2
	v_cvt_pk_bf16_f32 v96, v100, v101
	s_nop 2
	v_cvt_pk_bf16_f32 v97, v102, v103
	s_nop 2
	v_cvt_pk_bf16_f32 v98, v98, v99
	s_nop 2
	v_cvt_pk_bf16_f32 v99, v104, v105
	global_store_dwordx4 v[116:117], v[96:99], off offset:256
	global_load_dwordx4 v[96:99], v[110:111], off
	v_lshl_add_u64 v[100:101], s[86:87], 0, v[108:109]
	s_waitcnt vmcnt(0)
	v_lshlrev_b32_e32 v102, 16, v96
	v_and_b32_e32 v103, 0xffff0000, v96
	v_lshlrev_b32_e32 v96, 16, v97
	v_and_b32_e32 v97, 0xffff0000, v97
	v_lshlrev_b32_e32 v104, 16, v98
	v_and_b32_e32 v105, 0xffff0000, v98
	v_lshlrev_b32_e32 v98, 16, v99
	v_and_b32_e32 v99, 0xffff0000, v99
	v_pk_add_f32 v[94:95], v[94:95], v[96:97]
	v_pk_add_f32 v[96:97], v[90:91], v[98:99]
	v_pk_add_f32 v[90:91], v[88:89], v[104:105]
	v_pk_add_f32 v[92:93], v[92:93], v[102:103]
	s_nop 0
	v_cvt_pk_bf16_f32 v88, v92, v93
	v_cvt_pk_bf16_f32 v89, v94, v95
	v_cvt_pk_bf16_f32 v90, v90, v91
	v_cvt_pk_bf16_f32 v91, v96, v97
	global_store_dwordx4 v[100:101], v[88:91], off
	global_load_dwordx4 v[88:91], v[110:111], off offset:256
	v_or_b32_e32 v92, 48, v148
	v_ashrrev_i32_e32 v93, 31, v92
	v_lshlrev_b64 v[92:93], 12, v[92:93]
	v_lshl_add_u64 v[92:93], v[92:93], 0, v[146:147]
	v_lshlrev_b64 v[92:93], 1, v[92:93]
	v_lshl_add_u64 v[94:95], s[74:75], 0, v[92:93]
	s_waitcnt vmcnt(0)
	v_lshlrev_b32_e32 v96, 16, v88
	v_and_b32_e32 v97, 0xffff0000, v88
	v_lshlrev_b32_e32 v88, 16, v89
	v_and_b32_e32 v89, 0xffff0000, v89
	v_lshlrev_b32_e32 v98, 16, v90
	v_and_b32_e32 v99, 0xffff0000, v90
	v_lshlrev_b32_e32 v90, 16, v91
	v_and_b32_e32 v91, 0xffff0000, v91
	v_pk_add_f32 v[86:87], v[86:87], v[88:89]
	v_pk_add_f32 v[88:89], v[82:83], v[90:91]
	v_pk_add_f32 v[82:83], v[80:81], v[98:99]
	v_pk_add_f32 v[84:85], v[84:85], v[96:97]
	s_nop 0
	v_cvt_pk_bf16_f32 v80, v84, v85
	v_cvt_pk_bf16_f32 v81, v86, v87
	v_cvt_pk_bf16_f32 v82, v82, v83
	v_cvt_pk_bf16_f32 v83, v88, v89
	global_store_dwordx4 v[100:101], v[80:83], off offset:256
	global_load_dwordx4 v[80:83], v[94:95], off
	v_lshl_add_u64 v[84:85], s[86:87], 0, v[92:93]
	s_waitcnt vmcnt(0)
	v_lshlrev_b32_e32 v86, 16, v80
	v_and_b32_e32 v87, 0xffff0000, v80
	v_lshlrev_b32_e32 v80, 16, v81
	v_and_b32_e32 v81, 0xffff0000, v81
	v_lshlrev_b32_e32 v88, 16, v82
	v_and_b32_e32 v89, 0xffff0000, v82
	v_lshlrev_b32_e32 v82, 16, v83
	v_and_b32_e32 v83, 0xffff0000, v83
	v_pk_add_f32 v[78:79], v[78:79], v[80:81]
	v_pk_add_f32 v[80:81], v[74:75], v[82:83]
	v_pk_add_f32 v[74:75], v[72:73], v[88:89]
	v_pk_add_f32 v[76:77], v[76:77], v[86:87]
	s_nop 0
	v_cvt_pk_bf16_f32 v72, v76, v77
	v_cvt_pk_bf16_f32 v73, v78, v79
	v_cvt_pk_bf16_f32 v74, v74, v75
	v_cvt_pk_bf16_f32 v75, v80, v81
	global_store_dwordx4 v[84:85], v[72:75], off
	global_load_dwordx4 v[72:75], v[94:95], off offset:256
	v_lshl_add_u64 v[76:77], v[144:145], 0, s[16:17]
	v_lshl_add_u64 v[78:79], s[74:75], 0, v[76:77]
	s_waitcnt vmcnt(0)
	v_lshlrev_b32_e32 v80, 16, v72
	v_and_b32_e32 v81, 0xffff0000, v72
	v_lshlrev_b32_e32 v72, 16, v73
	v_and_b32_e32 v73, 0xffff0000, v73
	v_lshlrev_b32_e32 v82, 16, v74
	v_and_b32_e32 v83, 0xffff0000, v74
	v_lshlrev_b32_e32 v74, 16, v75
	v_and_b32_e32 v75, 0xffff0000, v75
	v_pk_add_f32 v[70:71], v[70:71], v[72:73]
	v_pk_add_f32 v[72:73], v[66:67], v[74:75]
	v_pk_add_f32 v[66:67], v[64:65], v[82:83]
	v_pk_add_f32 v[68:69], v[68:69], v[80:81]
	s_nop 0
	v_cvt_pk_bf16_f32 v64, v68, v69
	v_cvt_pk_bf16_f32 v65, v70, v71
	v_cvt_pk_bf16_f32 v66, v66, v67
	v_cvt_pk_bf16_f32 v67, v72, v73
	global_store_dwordx4 v[84:85], v[64:67], off offset:256
	global_load_dwordx4 v[64:67], v[78:79], off
	v_lshl_add_u64 v[68:69], s[86:87], 0, v[76:77]
	s_waitcnt vmcnt(0)
	v_lshlrev_b32_e32 v70, 16, v64
	v_and_b32_e32 v71, 0xffff0000, v64
	v_lshlrev_b32_e32 v64, 16, v65
	v_and_b32_e32 v65, 0xffff0000, v65
	v_lshlrev_b32_e32 v72, 16, v66
	v_and_b32_e32 v73, 0xffff0000, v66
	v_lshlrev_b32_e32 v66, 16, v67
	v_and_b32_e32 v67, 0xffff0000, v67
	v_pk_add_f32 v[62:63], v[62:63], v[64:65]
	v_pk_add_f32 v[64:65], v[58:59], v[66:67]
	v_pk_add_f32 v[58:59], v[56:57], v[72:73]
	v_pk_add_f32 v[60:61], v[60:61], v[70:71]
	s_nop 0
	v_cvt_pk_bf16_f32 v56, v60, v61
	v_cvt_pk_bf16_f32 v57, v62, v63
	v_cvt_pk_bf16_f32 v58, v58, v59
	v_cvt_pk_bf16_f32 v59, v64, v65
	global_store_dwordx4 v[68:69], v[56:59], off
	global_load_dwordx4 v[56:59], v[78:79], off offset:256
	v_lshl_add_u64 v[60:61], v[144:145], 0, s[18:19]
	v_lshl_add_u64 v[62:63], s[74:75], 0, v[60:61]
	s_waitcnt vmcnt(0)
	v_lshlrev_b32_e32 v64, 16, v56
	v_and_b32_e32 v65, 0xffff0000, v56
	v_lshlrev_b32_e32 v56, 16, v57
	v_and_b32_e32 v57, 0xffff0000, v57
	v_lshlrev_b32_e32 v66, 16, v58
	v_and_b32_e32 v67, 0xffff0000, v58
	v_lshlrev_b32_e32 v58, 16, v59
	v_and_b32_e32 v59, 0xffff0000, v59
	v_pk_add_f32 v[54:55], v[54:55], v[56:57]
	v_pk_add_f32 v[56:57], v[50:51], v[58:59]
	v_pk_add_f32 v[50:51], v[48:49], v[66:67]
	v_pk_add_f32 v[52:53], v[52:53], v[64:65]
	s_nop 0
	v_cvt_pk_bf16_f32 v48, v52, v53
	v_cvt_pk_bf16_f32 v49, v54, v55
	v_cvt_pk_bf16_f32 v50, v50, v51
	v_cvt_pk_bf16_f32 v51, v56, v57
	global_store_dwordx4 v[68:69], v[48:51], off offset:256
	global_load_dwordx4 v[48:51], v[62:63], off
	v_lshl_add_u64 v[52:53], s[86:87], 0, v[60:61]
	s_waitcnt vmcnt(0)
	v_lshlrev_b32_e32 v54, 16, v48
	v_and_b32_e32 v55, 0xffff0000, v48
	v_lshlrev_b32_e32 v48, 16, v49
	v_and_b32_e32 v49, 0xffff0000, v49
	v_lshlrev_b32_e32 v56, 16, v50
	v_and_b32_e32 v57, 0xffff0000, v50
	v_lshlrev_b32_e32 v50, 16, v51
	v_and_b32_e32 v51, 0xffff0000, v51
	v_pk_add_f32 v[46:47], v[46:47], v[48:49]
	v_pk_add_f32 v[48:49], v[42:43], v[50:51]
	v_pk_add_f32 v[42:43], v[40:41], v[56:57]
	v_pk_add_f32 v[44:45], v[44:45], v[54:55]
	s_nop 0
	v_cvt_pk_bf16_f32 v40, v44, v45
	v_cvt_pk_bf16_f32 v41, v46, v47
	v_cvt_pk_bf16_f32 v42, v42, v43
	v_cvt_pk_bf16_f32 v43, v48, v49
	global_store_dwordx4 v[52:53], v[40:43], off
	global_load_dwordx4 v[40:43], v[62:63], off offset:256
	v_lshl_add_u64 v[44:45], v[144:145], 0, s[20:21]
	v_lshl_add_u64 v[46:47], s[74:75], 0, v[44:45]
	s_waitcnt vmcnt(0)
	v_lshlrev_b32_e32 v48, 16, v40
	v_and_b32_e32 v49, 0xffff0000, v40
	v_lshlrev_b32_e32 v40, 16, v41
	v_and_b32_e32 v41, 0xffff0000, v41
	v_lshlrev_b32_e32 v50, 16, v42
	v_and_b32_e32 v51, 0xffff0000, v42
	v_lshlrev_b32_e32 v42, 16, v43
	v_and_b32_e32 v43, 0xffff0000, v43
	v_pk_add_f32 v[38:39], v[38:39], v[40:41]
	v_pk_add_f32 v[40:41], v[34:35], v[42:43]
	v_pk_add_f32 v[34:35], v[32:33], v[50:51]
	v_pk_add_f32 v[36:37], v[36:37], v[48:49]
	s_nop 0
	v_cvt_pk_bf16_f32 v32, v36, v37
	v_cvt_pk_bf16_f32 v33, v38, v39
	v_cvt_pk_bf16_f32 v34, v34, v35
	v_cvt_pk_bf16_f32 v35, v40, v41
	global_store_dwordx4 v[52:53], v[32:35], off offset:256
	global_load_dwordx4 v[32:35], v[46:47], off
	v_lshl_add_u64 v[36:37], s[86:87], 0, v[44:45]
	s_waitcnt vmcnt(0)
	v_lshlrev_b32_e32 v38, 16, v32
	v_and_b32_e32 v39, 0xffff0000, v32
	v_lshlrev_b32_e32 v32, 16, v33
	v_and_b32_e32 v33, 0xffff0000, v33
	v_lshlrev_b32_e32 v40, 16, v34
	v_and_b32_e32 v41, 0xffff0000, v34
	v_lshlrev_b32_e32 v34, 16, v35
	v_and_b32_e32 v35, 0xffff0000, v35
	v_pk_add_f32 v[30:31], v[30:31], v[32:33]
	v_pk_add_f32 v[32:33], v[26:27], v[34:35]
	v_pk_add_f32 v[26:27], v[24:25], v[40:41]
	v_pk_add_f32 v[28:29], v[28:29], v[38:39]
	s_nop 0
	v_cvt_pk_bf16_f32 v24, v28, v29
	v_cvt_pk_bf16_f32 v25, v30, v31
	v_cvt_pk_bf16_f32 v26, v26, v27
	v_cvt_pk_bf16_f32 v27, v32, v33
	global_store_dwordx4 v[36:37], v[24:27], off
	global_load_dwordx4 v[24:27], v[46:47], off offset:256
	v_lshl_add_u64 v[28:29], v[144:145], 0, s[22:23]
	v_lshl_add_u64 v[30:31], s[74:75], 0, v[28:29]
	s_waitcnt vmcnt(0)
	v_lshlrev_b32_e32 v32, 16, v24
	v_and_b32_e32 v33, 0xffff0000, v24
	v_lshlrev_b32_e32 v24, 16, v25
	v_and_b32_e32 v25, 0xffff0000, v25
	v_lshlrev_b32_e32 v34, 16, v26
	v_and_b32_e32 v35, 0xffff0000, v26
	v_lshlrev_b32_e32 v26, 16, v27
	v_and_b32_e32 v27, 0xffff0000, v27
	v_pk_add_f32 v[22:23], v[22:23], v[24:25]
	v_pk_add_f32 v[24:25], v[18:19], v[26:27]
	v_pk_add_f32 v[18:19], v[16:17], v[34:35]
	v_pk_add_f32 v[20:21], v[20:21], v[32:33]
	s_nop 0
	v_cvt_pk_bf16_f32 v16, v20, v21
	v_cvt_pk_bf16_f32 v17, v22, v23
	v_cvt_pk_bf16_f32 v18, v18, v19
	v_cvt_pk_bf16_f32 v19, v24, v25
	global_store_dwordx4 v[36:37], v[16:19], off offset:256
	global_load_dwordx4 v[16:19], v[30:31], off
	v_lshl_add_u64 v[20:21], s[86:87], 0, v[28:29]
	s_waitcnt vmcnt(0)
	v_lshlrev_b32_e32 v22, 16, v16
	v_and_b32_e32 v23, 0xffff0000, v16
	v_lshlrev_b32_e32 v16, 16, v17
	v_and_b32_e32 v17, 0xffff0000, v17
	v_lshlrev_b32_e32 v24, 16, v18
	v_and_b32_e32 v25, 0xffff0000, v18
	v_lshlrev_b32_e32 v18, 16, v19
	v_and_b32_e32 v19, 0xffff0000, v19
	v_pk_add_f32 v[14:15], v[14:15], v[16:17]
	v_pk_add_f32 v[16:17], v[10:11], v[18:19]
	v_pk_add_f32 v[10:11], v[8:9], v[24:25]
	v_pk_add_f32 v[12:13], v[12:13], v[22:23]
	s_nop 0
	v_cvt_pk_bf16_f32 v8, v12, v13
	v_cvt_pk_bf16_f32 v9, v14, v15
	v_cvt_pk_bf16_f32 v10, v10, v11
	v_cvt_pk_bf16_f32 v11, v16, v17
	global_store_dwordx4 v[20:21], v[8:11], off
	global_load_dwordx4 v[8:11], v[30:31], off offset:256
	s_waitcnt vmcnt(0)
	v_lshlrev_b32_e32 v12, 16, v8
	v_and_b32_e32 v13, 0xffff0000, v8
	v_lshlrev_b32_e32 v8, 16, v9
	v_and_b32_e32 v9, 0xffff0000, v9
	v_lshlrev_b32_e32 v14, 16, v10
	v_and_b32_e32 v15, 0xffff0000, v10
	v_lshlrev_b32_e32 v10, 16, v11
	v_and_b32_e32 v11, 0xffff0000, v11
	v_pk_add_f32 v[6:7], v[6:7], v[8:9]
	v_pk_add_f32 v[8:9], v[2:3], v[10:11]
	v_pk_add_f32 v[2:3], v[0:1], v[14:15]
	v_pk_add_f32 v[4:5], v[4:5], v[12:13]
	s_nop 0
	v_cvt_pk_bf16_f32 v0, v4, v5
	v_cvt_pk_bf16_f32 v1, v6, v7
	v_cvt_pk_bf16_f32 v2, v2, v3
	v_cvt_pk_bf16_f32 v3, v8, v9
	global_store_dwordx4 v[20:21], v[0:3], off offset:256
	s_cbranch_vccnz .LBB0_1065
	s_andn2_b64 vcc, exec, s[8:9]
	s_cbranch_vccnz .LBB0_1064
	s_barrier
	s_branch .LBB0_1064

.LBB0_1312:
	s_ashr_i32 s29, s28, 31
	s_lshl_b64 s[30:31], s[28:29], 21
	s_add_u32 s30, s86, s30
	s_addc_u32 s31, s87, s31
	s_and_b64 s[34:35], s[4:5], exec
	s_cselect_b32 s14, s31, s41
	s_cselect_b32 s29, s30, s40
	s_ashr_i32 s27, s26, 31
	s_lshl_b64 s[34:35], s[26:27], 21
	v_readlane_b32 s27, v254, 0
	s_add_u32 s36, s27, s34
	s_addc_u32 s37, s33, s35
	s_and_b64 s[34:35], s[4:5], exec
	s_cselect_b32 s27, s37, s43
	s_cselect_b32 s39, s36, s42
	s_add_u32 s40, s40, 0x100080
	s_addc_u32 s41, s41, 0
	s_add_u32 s34, s42, 0x100
	v_mov_b32_e32 v0, 0
	s_addc_u32 s35, s43, 0
	s_mov_b32 s60, -2
	s_waitcnt lgkmcnt(0)
	v_mov_b32_e32 v1, v0
	v_mov_b64_e32 v[2:3], 0
	v_mov_b64_e32 v[4:5], 0
	v_mov_b64_e32 v[6:7], 0
	v_mov_b64_e32 v[8:9], 0
	v_mov_b64_e32 v[10:11], 0
	v_mov_b64_e32 v[12:13], 0
	v_mov_b64_e32 v[14:15], 0
	v_mov_b64_e32 v[16:17], 0
	v_mov_b64_e32 v[18:19], 0
	v_mov_b64_e32 v[20:21], 0
	v_mov_b64_e32 v[22:23], 0
	v_mov_b64_e32 v[24:25], 0
	v_mov_b64_e32 v[26:27], 0
	v_mov_b64_e32 v[28:29], 0
	v_mov_b64_e32 v[30:31], 0
	v_mov_b64_e32 v[32:33], 0
	v_mov_b64_e32 v[34:35], 0
	v_mov_b64_e32 v[36:37], 0
	v_mov_b64_e32 v[38:39], 0
	v_mov_b64_e32 v[40:41], 0
	v_mov_b64_e32 v[42:43], 0
	v_mov_b64_e32 v[44:45], 0
	v_mov_b64_e32 v[46:47], 0
	v_mov_b64_e32 v[56:57], 0
	v_mov_b64_e32 v[58:59], 0
	v_mov_b64_e32 v[60:61], 0
	v_mov_b64_e32 v[62:63], 0
	v_mov_b64_e32 v[64:65], 0
	v_mov_b64_e32 v[66:67], 0
	v_mov_b64_e32 v[68:69], 0
	v_mov_b64_e32 v[70:71], 0
	v_mov_b64_e32 v[72:73], 0
	v_mov_b64_e32 v[74:75], 0
	v_mov_b64_e32 v[76:77], 0
	v_mov_b64_e32 v[78:79], 0
	v_mov_b64_e32 v[80:81], 0
	v_mov_b64_e32 v[82:83], 0
	v_mov_b64_e32 v[84:85], 0
	v_mov_b64_e32 v[86:87], 0
	v_mov_b64_e32 v[88:89], 0
	v_mov_b64_e32 v[90:91], 0
	v_mov_b64_e32 v[92:93], 0
	v_mov_b64_e32 v[94:95], 0
	v_mov_b64_e32 v[96:97], 0
	v_mov_b64_e32 v[98:99], 0
	v_mov_b64_e32 v[100:101], 0
	v_mov_b64_e32 v[102:103], 0
	v_mov_b64_e32 v[104:105], 0
	v_mov_b64_e32 v[106:107], 0
	v_mov_b64_e32 v[108:109], 0
	v_mov_b64_e32 v[110:111], 0
	v_mov_b64_e32 v[112:113], 0
	v_mov_b64_e32 v[114:115], 0
	v_mov_b64_e32 v[116:117], 0
	v_mov_b64_e32 v[118:119], 0
	v_mov_b64_e32 v[120:121], 0
	v_mov_b64_e32 v[122:123], 0
	v_mov_b64_e32 v[124:125], 0
	v_mov_b64_e32 v[126:127], 0
	v_mov_b64_e32 v[128:129], 0
	v_mov_b64_e32 v[130:131], 0
	v_mov_b64_e32 v[132:133], 0
	v_mov_b64_e32 v[134:135], 0
	s_cmpk_lt_u32 s97, 0x100
	s_cbranch_scc1 .Lmy_prio_skip7
	s_setprio 1
